# ssd_out: row blocks permuted across waves (w<4 -> 7-w, else w-4) so each SIMD's two waves carry equal causal work
# baseline (speedup 1.0000x reference)
; DI void ssd_out_unit(const Params& p, int layer, int hf, int bl, int c, unsigned char* shm, int tid, bool dry = false) {
;   unsigned char* wsb = ows(p);
;   constexpr int LXS = 72;
;   bf16_t* sC = (bf16_t*)shm; bf16_t* sB = sC + 128 * LD; bf16_t* sM = sB; bf16_t* sX = sB + 128 * LD; bf16_t* sSp = sX + 128 * LXS;
;   float* sDt = (float*)(sSp + 64 * LD); float* sAc = sDt + 16 * 128;
;   bf16_t* projb = (bf16_t*)(wsb + WS_PROJ) + (size_t)bl * SEQ * NP;
;   const bf16_t* xcb = (const bf16_t*)(wsb + WS_XC) + (size_t)(bl * SEQ + c * 128) * 1536;
;   const float* tail = (const float*)(wsb + WS_TAIL) + (size_t)((hf * 2 + bl) * SEQ + c * 128) * 24;
;   const int wid = tid >> 6, lane = tid & 63, fr = lane & 15, fq = lane >> 4;
;   const int i_row = 16 * wid + fr;
; #pragma unroll
;   for (int q = 0; q < 2; ++q) {
;     const int h = 2 * wid + q; const float Ah = -__expf(p.a_log[layer * 16 + h]);
;     const float d0 = tail[(2 * lane) * 24 + h], d1 = tail[(2 * lane + 1) * 24 + h];
;     float c0, c1, last; wave_cumsum128(d0 * Ah, d1 * Ah, lane, c0, c1, last);
;     sDt[h * 128 + 2 * lane] = d0; sDt[h * 128 + 2 * lane + 1] = d1; sAc[h * 128 + 2 * lane] = c0; sAc[h * 128 + 2 * lane + 1] = c1;
;   }
.LBB0_501:
	s_lshr_b32 s16, s16, 6
	v_mov_b32_e32 v1, v163
	s_mul_i32 s2, s16, 0x3400000
	v_writelane_b32 v254, s23, 63
	s_and_b32 s17, s23, 63
	s_lshl_b64 s[0:1], s[2:3], 1
	v_ashrrev_i32_e32 v10, 6, v1
	v_sub_u32_e32 v160, 7, v10
	v_cmp_gt_u32_e32 vcc, 4, v10
	v_add_u32_e32 v10, -4, v10
	s_nop 1
	v_cndmask_b32_e32 v10, v10, v160, vcc
	s_add_u32 s12, s38, s0
	v_writelane_b32 v255, s0, 0
	v_lshlrev_b32_e32 v4, 1, v10
	v_readlane_b32 s18, v254, 24
	v_writelane_b32 v255, s1, 1
	s_addc_u32 s13, s39, s1
	s_lshl_b32 s0, s16, 13
	s_lshl_b32 s19, s17, 7
	v_add_u32_e32 v2, s18, v4
	v_readlane_b32 s44, v252, 24
	s_or_b32 s1, s0, s19
	s_add_i32 s0, s0, s68
	v_ashrrev_i32_e32 v3, 31, v2
	v_readlane_b32 s48, v252, 28
	v_readlane_b32 s49, v252, 29
	s_or_b32 s0, s0, s19
	s_mul_i32 s2, s1, 0x600
	v_lshl_add_u64 v[2:3], v[2:3], 2, s[48:49]
	s_mul_i32 s0, s0, 24
	s_mov_b32 s1, s3
	global_load_dwordx2 v[2:3], v[2:3], off
	s_lshl_b64 s[0:1], s[0:1], 2
	v_and_b32_e32 v0, 63, v1
	s_add_u32 s14, s62, s0
	v_mad_u32_u24 v8, v0, 48, v4
	s_addc_u32 s15, s63, s1
	v_ashrrev_i32_e32 v9, 31, v8
	v_lshl_add_u64 v[8:9], v[8:9], 2, s[14:15]
	global_load_dwordx2 v[12:13], v[8:9], off
	s_nop 0
	global_load_dwordx2 v[8:9], v[8:9], off offset:96
	v_lshlrev_b32_e32 v120, 2, v0
	v_add_u32_e32 v11, -4, v120
	v_cmp_eq_u32_e64 s[10:11], 0, v0
	v_add_u32_e32 v18, -8, v120
	v_cmp_gt_u32_e64 s[8:9], 2, v0
	v_add_u32_e32 v19, -16, v120
	v_cmp_gt_u32_e64 s[6:7], 4, v0
	v_subrev_u32_e32 v20, 32, v120
	v_cmp_gt_u32_e64 s[4:5], 8, v0
	v_subrev_u32_e32 v21, 64, v120
	v_cmp_gt_u32_e64 s[0:1], 16, v0
	v_add_u32_e32 v22, 0xffffff80, v120
	v_cmp_gt_u32_e32 vcc, 32, v0
	v_lshlrev_b32_e32 v0, 3, v0
	v_lshl_or_b32 v0, v10, 10, v0
	v_readlane_b32 s14, v254, 2
	v_readlane_b32 s15, v254, 3
	v_and_b32_e32 v113, 15, v1
	v_lshlrev_b32_e32 v117, 4, v10
	v_mov_b32_e32 v87, v161
	v_writelane_b32 v255, s68, 2
	v_writelane_b32 v255, s19, 3
	v_and_b32_e32 v160, 48, v1
	v_readlane_b32 s50, v252, 30
	v_readlane_b32 s51, v252, 31
	v_readlane_b32 s52, v252, 32
	v_readlane_b32 s53, v252, 33
	v_readlane_b32 s54, v252, 34
	v_readlane_b32 s55, v252, 35
	v_readlane_b32 s56, v252, 36
	v_readlane_b32 s57, v252, 37
	v_readlane_b32 s58, v252, 38
	v_readlane_b32 s59, v252, 39
	s_mov_b32 s43, 0
	v_add_u32_e32 v126, s15, v160
	v_add_u32_e32 v127, s14, v160
	v_cmp_lt_i32_e64 s[48:49], 2, v10
	v_cmp_lt_i32_e64 s[52:53], 3, v10
	v_cmp_lt_i32_e64 s[54:55], 4, v10
	v_cmp_lt_i32_e64 s[56:57], 5, v10
	v_cmp_lt_i32_e64 s[58:59], 6, v10
	s_mov_b64 s[30:31], -1
	v_mov_b32_e32 v134, 0
	v_readlane_b32 s45, v252, 25
	v_readlane_b32 s46, v252, 26
	v_readlane_b32 s47, v252, 27
	s_waitcnt vmcnt(2)
	v_mul_f32_e32 v2, 0x3fb8aa3b, v2
	v_exp_f32_e32 v5, v2
	v_add_u32_e32 v2, s14, v0
	v_xor_b32_e32 v6, 0x80000000, v5
	s_waitcnt vmcnt(1)
	v_mov_b32_e32 v4, v12
	s_waitcnt vmcnt(0)
	v_mov_b32_e32 v7, v8
	v_pk_mul_f32 v[14:15], v[4:5], v[6:7]
	v_mov_b32_e32 v16, v12
	v_pk_fma_f32 v[4:5], v[4:5], v[6:7], v[14:15] op_sel:[0,0,1] op_sel_hi:[1,1,0] neg_lo:[0,0,1] neg_hi:[0,0,1]
	ds_bpermute_b32 v6, v11, v4
	v_mov_b32_e32 v17, v8
	ds_write_b64 v2, v[16:17]
	v_add_u32_e32 v2, s15, v0
	v_or_b32_e32 v0, 0x200, v0
	s_waitcnt lgkmcnt(1)
	v_add_f32_e32 v6, v4, v6
	v_cndmask_b32_e64 v6, v6, v4, s[10:11]
	ds_bpermute_b32 v7, v18, v6
	v_add_u32_e32 v12, s14, v0
	v_add_u32_e32 v0, s15, v0
	v_ashrrev_i32_e32 v17, 4, v1
	s_waitcnt lgkmcnt(0)
	v_add_f32_e32 v7, v6, v7
	v_cndmask_b32_e64 v6, v7, v6, s[8:9]
	ds_bpermute_b32 v7, v19, v6
	s_waitcnt lgkmcnt(0)
	v_add_f32_e32 v7, v6, v7
	v_cndmask_b32_e64 v6, v7, v6, s[6:7]
	ds_bpermute_b32 v7, v20, v6
	s_waitcnt lgkmcnt(0)
	v_add_f32_e32 v7, v6, v7
	v_cndmask_b32_e64 v6, v7, v6, s[4:5]
	ds_bpermute_b32 v7, v21, v6
	s_waitcnt lgkmcnt(0)
	v_add_f32_e32 v7, v6, v7
	v_cndmask_b32_e64 v6, v7, v6, s[0:1]
	ds_bpermute_b32 v7, v22, v6
	s_waitcnt lgkmcnt(0)
	v_add_f32_e32 v7, v6, v7
	v_cndmask_b32_e32 v6, v7, v6, vcc
	v_sub_f32_e32 v15, v6, v4
	v_pk_mov_b32 v[4:5], v[14:15], v[4:5] op_sel:[1,0]
	v_mov_b32_e32 v6, v13
	v_pk_add_f32 v[4:5], v[14:15], v[4:5]
	ds_write_b64 v2, v[4:5]
	v_mul_f32_e32 v2, 0x3fb8aa3b, v3
	v_exp_f32_e32 v3, v2
	v_mov_b32_e32 v2, v13
	v_mov_b32_e32 v7, v9
	ds_write_b64 v12, v[6:7]
	v_xor_b32_e32 v8, 0x80000000, v3
	v_pk_mul_f32 v[4:5], v[2:3], v[8:9]
	v_or_b32_e32 v13, v117, v113
	v_pk_fma_f32 v[2:3], v[2:3], v[8:9], v[4:5] op_sel:[0,0,1] op_sel_hi:[1,1,0] neg_lo:[0,0,1] neg_hi:[0,0,1]
	ds_bpermute_b32 v5, v11, v2
	v_and_b32_e32 v14, 7, v1
	v_mov_b32_e32 v7, v161
	v_bfe_u32 v12, v1, 4, 2
	v_lshlrev_b32_e32 v86, 3, v12
	s_waitcnt lgkmcnt(0)
	v_add_f32_e32 v5, v2, v5
	v_cndmask_b32_e64 v5, v5, v2, s[10:11]
	ds_bpermute_b32 v6, v18, v5
	v_mov_b32_e32 v15, v161
	v_add_u32_e32 v11, 32, v160
	v_lshl_add_u32 v125, v13, 2, s15
	s_waitcnt lgkmcnt(0)
	v_add_f32_e32 v6, v5, v6
	v_cndmask_b32_e64 v5, v6, v5, s[8:9]
	ds_bpermute_b32 v6, v19, v5
	s_movk_i32 s8, 0x1100
	s_waitcnt lgkmcnt(0)
	v_add_f32_e32 v6, v5, v6
	v_cndmask_b32_e64 v5, v6, v5, s[6:7]
	ds_bpermute_b32 v6, v20, v5
	v_readlane_b32 s6, v254, 0
	v_readlane_b32 s7, v254, 4
	s_waitcnt lgkmcnt(0)
	v_add_f32_e32 v6, v5, v6
	v_cndmask_b32_e64 v5, v6, v5, s[4:5]
	ds_bpermute_b32 v6, v21, v5
	v_add_u32_e32 v16, s7, v160
	s_waitcnt lgkmcnt(0)
	v_add_f32_e32 v6, v5, v6
	v_cndmask_b32_e64 v5, v6, v5, s[0:1]
	ds_bpermute_b32 v6, v22, v5
	s_lshl_b64 s[0:1], s[2:3], 1
	s_add_u32 s0, s33, s0
	s_addc_u32 s1, s64, s1
	s_movk_i32 s2, 0x90
	s_waitcnt lgkmcnt(0)
; DI void ssd_out_unit(const Params& p, int layer, int hf, int bl, int c, unsigned char* shm, int tid, bool dry = false) {
;     ...
;     const int xj0 = tid >> 3, xpg = tid & 7;
;     {
;       const int h0 = g * 8;
;       xr0 = *(const uint4*)(xcb + (size_t)xj0 * 1536 + h0 * 64 + xpg * 8); xr1 = *(const uint4*)(xcb + (size_t)(xj0 + 64) * 1536 + h0 * 64 + xpg * 8);
;       const bf16_t* st = (const bf16_t*)(wsb + WS_SSTP + (size_t)hf * HROWS * DM * 2) + (size_t)((bl * 64 + c) * 16 + h0) * 8192 + xj0 * 128 + xpg * 16;
;       sr0 = *(const uint4*)(st); sr1 = *(const uint4*)(st + 8);
;     }
;     for (int hh = 0; hh < 8; ++hh) {
;       const int h = g * 8 + hh;
;       *(uint4*)(sX + xj0 * LXS + xpg * 8) = xr0; *(uint4*)(sX + (xj0 + 64) * LXS + xpg * 8) = xr1;
;       *(uint4*)(sSp + xj0 * LD + xpg * 16) = sr0; *(uint4*)(sSp + xj0 * LD + xpg * 16 + 8) = sr1;
;       {
;         const int h1 = (hh + 1 < 8) ? h + 1 : h;
;         xr0 = *(const uint4*)(xcb + (size_t)xj0 * 1536 + h1 * 64 + xpg * 8); xr1 = *(const uint4*)(xcb + (size_t)(xj0 + 64) * 1536 + h1 * 64 + xpg * 8);
;         const bf16_t* st = (const bf16_t*)(wsb + WS_SSTP + (size_t)hf * HROWS * DM * 2) + (size_t)((bl * 64 + c) * 16 + h1) * 8192 + xj0 * 128 + xpg * 16;
;         sr0 = *(const uint4*)(st); sr1 = *(const uint4*)(st + 8);
;       }
;       const float ac_i = sAc[h * 128 + i_row];
; #pragma unroll
;       for (int n = 0; n < 8; ++n) {
;         if (n <= (wid | 1)) {
;           uint2 w; w.x = 0u; w.y = 0u;
;           if (n <= wid) {
;             const float4 acj = *(const float4*)(sAc + h * 128 + 16 * n + 4 * fq), dtj = *(const float4*)(sDt + h * 128 + 16 * n + 4 * fq);
;             const int j0 = 16 * n + 4 * fq;
;             const float r0 = (j0 + 0 <= i_row) ? cbv[n][0] * __expf(ac_i - acj.x) * dtj.x : 0.f;
;             const float r1 = (j0 + 1 <= i_row) ? cbv[n][1] * __expf(ac_i - acj.y) * dtj.y : 0.f;
;             const float r2 = (j0 + 2 <= i_row) ? cbv[n][2] * __expf(ac_i - acj.z) * dtj.z : 0.f;
;             const float r3 = (j0 + 3 <= i_row) ? cbv[n][3] * __expf(ac_i - acj.w) * dtj.w : 0.f;
;             w.x = pk2(r0, r1); w.y = pk2(r2, r3);
;           }
;           *(uint2*)(sM + i_row * LD + 16 * n + 4 * fq) = w;
;         }
;       }
;       bf16_t* zp = projb + (size_t)(c * 128 + i_row) * NP + C_Z + h * 64 + 4 * fq;
;       uint2 zv4[4];
; #pragma unroll
	v_add_f32_e32 v6, v5, v6
	v_cndmask_b32_e32 v5, v6, v5, vcc
	v_sub_f32_e32 v5, v5, v2
	v_pk_mov_b32 v[2:3], v[4:5], v[2:3] op_sel:[1,0]
	v_lshlrev_b32_e32 v6, 4, v14
	v_pk_add_f32 v[2:3], v[4:5], v[2:3]
	ds_write_b64 v0, v[2:3]
	v_mul_lo_u32 v3, v13, s66
	v_add_u32_e32 v121, 32, v3
	v_ashrrev_i32_e32 v3, 3, v1
	v_mov_b64_e32 v[4:5], s[0:1]
	v_mad_i64_i32 v[8:9], s[0:1], v3, s67, v[4:5]
	v_lshl_add_u64 v[80:81], v[8:9], 0, v[6:7]
	v_add_u32_e32 v8, 64, v3
	v_mad_i64_i32 v[8:9], s[0:1], v8, s67, v[4:5]
	s_lshl_b32 s0, s16, 10
	s_lshl_b32 s1, s17, 4
	v_lshl_add_u64 v[82:83], v[8:9], 0, v[6:7]
	s_or_b32 s33, s0, s1
	v_lshlrev_b32_e32 v8, 7, v3
	v_readlane_b32 s0, v254, 51
	v_lshlrev_b32_e32 v14, 5, v14
	v_mul_lo_u32 v7, v3, s2
	v_mul_lo_u32 v3, v3, s66
	v_ashrrev_i32_e32 v9, 31, v8
	v_readlane_b32 s1, v254, 52
	v_add3_u32 v122, s6, v7, v6
	v_add3_u32 v124, s7, v3, v14
	v_add_u32_e32 v3, s19, v13
	v_mov_b64_e32 v[6:7], s[12:13]
	v_lshl_add_u64 v[8:9], v[8:9], 1, s[0:1]
	v_mad_i64_i32 v[6:7], s[0:1], v3, s65, v[6:7]
	v_lshlrev_b32_e32 v0, 4, v1
	v_lshl_add_u64 v[6:7], v[6:7], 0, v[86:87]
	s_mov_b64 s[0:1], 0x2800
	v_mul_lo_u32 v3, v13, s2
	v_and_b32_e32 v2, 0xf0, v0
	v_lshl_add_u64 v[88:89], v[6:7], 0, s[0:1]
	v_add3_u32 v87, s6, v3, v86
	v_mad_i64_i32 v[6:7], s[0:1], v17, s67, v[4:5]
	v_mov_b32_e32 v3, v161
	v_add_u32_e32 v0, 32, v2
	v_lshl_add_u64 v[90:91], v[6:7], 0, v[2:3]
	v_add_u32_e32 v6, 0x200, v1
	v_mad_u64_u32 v[92:93], s[0:1], v17, s66, v[0:1]
	v_ashrrev_i32_e32 v17, 4, v6
	v_mad_i64_i32 v[6:7], s[0:1], v17, s67, v[4:5]
	v_lshl_add_u64 v[94:95], v[6:7], 0, v[2:3]
	v_add_u32_e32 v6, 0x400, v1
	v_mad_u64_u32 v[96:97], s[0:1], v17, s66, v[0:1]
	v_ashrrev_i32_e32 v17, 4, v6
	v_mad_i64_i32 v[6:7], s[0:1], v17, s67, v[4:5]
	v_lshl_add_u64 v[98:99], v[6:7], 0, v[2:3]
	v_add_u32_e32 v6, 0x600, v1
	v_ashrrev_i32_e32 v6, 4, v6
	v_lshl_add_u64 v[84:85], v[8:9], 0, v[14:15]
	v_lshlrev_b32_e32 v9, 2, v12
	v_mad_i64_i32 v[4:5], s[0:1], v6, s67, v[4:5]
	v_lshl_add_u64 v[102:103], v[4:5], 0, v[2:3]
	v_or_b32_e32 v2, 2, v9
	v_cmp_gt_i32_e64 s[26:27], v2, v13
	v_or_b32_e32 v2, 3, v9
	v_mad_u64_u32 v[100:101], s[0:1], v17, s66, v[0:1]
	v_mad_u64_u32 v[104:105], s[0:1], v6, s66, v[0:1]
	v_cmp_gt_i32_e64 s[28:29], v2, v13
	v_or_b32_e32 v2, 16, v9
	v_cmp_le_i32_e64 s[0:1], v2, v13
	s_movk_i32 s2, 0x110
	v_lshrrev_b32_e32 v14, 1, v10
	v_writelane_b32 v255, s0, 4
	v_bfe_u32 v15, v1, 2, 2
	v_and_b32_e32 v1, 3, v1
	v_writelane_b32 v255, s1, 5
	v_cmp_lt_i32_e64 s[0:1], v2, v13
	v_or_b32_e32 v2, 18, v9
	v_or_b32_e32 v8, 1, v10
	v_writelane_b32 v255, s0, 6
	v_mul_u32_u24_e32 v0, 0x110, v113
	v_mul_u32_u24_e32 v3, 0x90, v15
	v_writelane_b32 v255, s1, 7
	v_cmp_gt_i32_e64 s[0:1], v2, v13
	v_or_b32_e32 v2, 19, v9
	v_lshlrev_b32_e32 v1, 3, v1
	v_writelane_b32 v255, s0, 8
	v_add_u32_e32 v123, 0x2400, v122
	v_add_u32_e32 v128, v121, v86
	v_writelane_b32 v255, s1, 9
	v_cmp_gt_i32_e64 s[0:1], v2, v13
	v_or_b32_e32 v2, 32, v9
	v_cmp_lt_i32_e64 s[4:5], -1, v14
	v_writelane_b32 v255, s0, 10
	v_add_u32_e32 v93, 0x8800, v92
	v_add_u32_e32 v97, 0x8800, v96
	v_writelane_b32 v255, s1, 11
	v_cmp_le_i32_e64 s[0:1], v2, v13
	v_add_u32_e32 v101, 0x8800, v100
	v_add_u32_e32 v105, 0x8800, v104
	v_writelane_b32 v255, s0, 12
	v_cmp_lt_i32_e64 s[6:7], -1, v10
	v_cmp_lt_i32_e64 s[64:65], 0, v10
	v_writelane_b32 v255, s1, 13
	v_cmp_lt_i32_e64 s[0:1], v2, v13
	v_or_b32_e32 v2, 34, v9
	v_cmp_lt_i32_e64 s[66:67], 1, v10
	v_writelane_b32 v255, s0, 14
	v_cmp_le_i32_e64 s[62:63], v9, v13
	v_cmp_lt_i32_e64 s[24:25], v9, v13
	v_writelane_b32 v255, s1, 15
	v_cmp_gt_i32_e64 s[0:1], v2, v13
	v_or_b32_e32 v2, 35, v9
	v_cmp_lt_i32_e64 s[40:41], 1, v8
	v_writelane_b32 v255, s0, 16
	v_cmp_lt_i32_e64 s[50:51], 2, v8
	v_cmp_lt_i32_e64 s[60:61], 3, v8
	v_writelane_b32 v255, s1, 17
	v_cmp_gt_i32_e64 s[0:1], v2, v13
	v_or_b32_e32 v2, 48, v9
	v_cmp_lt_i32_e64 s[70:71], 4, v8
	v_writelane_b32 v255, s0, 18
	v_cmp_lt_i32_e64 s[80:81], 5, v8
	v_cmp_lt_i32_e64 s[90:91], 6, v8
	v_writelane_b32 v255, s1, 19
	v_cmp_le_i32_e64 s[0:1], v2, v13
	v_add_u32_e32 v129, 1, v14
	v_add_u32_e32 v132, v16, v0
	v_writelane_b32 v255, s0, 20
	v_add_u32_e32 v133, v11, v0
	s_nop 0
	v_writelane_b32 v255, s1, 21
	v_cmp_lt_i32_e64 s[0:1], v2, v13
	v_or_b32_e32 v2, 50, v9
	s_nop 0
	v_writelane_b32 v255, s0, 22
	s_nop 1
	v_writelane_b32 v255, s1, 23
	v_cmp_gt_i32_e64 s[0:1], v2, v13
	v_or_b32_e32 v2, 51, v9
	s_nop 0
	v_writelane_b32 v255, s0, 24
	s_nop 1
	v_writelane_b32 v255, s1, 25
	v_cmp_gt_i32_e64 s[0:1], v2, v13
	v_or_b32_e32 v2, 64, v9
	s_nop 0
	v_writelane_b32 v255, s0, 26
	s_nop 1
	v_writelane_b32 v255, s1, 27
	v_cmp_le_i32_e64 s[0:1], v2, v13
	s_nop 1
	v_writelane_b32 v255, s0, 28
	s_nop 1
	v_writelane_b32 v255, s1, 29
	v_cmp_lt_i32_e64 s[0:1], v2, v13
	v_or_b32_e32 v2, 0x42, v9
	s_nop 0
	v_writelane_b32 v255, s0, 30
	s_nop 1
	v_writelane_b32 v255, s1, 31
	v_cmp_gt_i32_e64 s[0:1], v2, v13
	v_or_b32_e32 v2, 0x43, v9
	v_cmp_gt_i32_e64 s[68:69], v2, v13
	v_or_b32_e32 v2, 0x50, v9
	v_cmp_le_i32_e64 s[72:73], v2, v13
	v_cmp_lt_i32_e64 s[74:75], v2, v13
	v_or_b32_e32 v2, 0x52, v9
	v_cmp_gt_i32_e64 s[76:77], v2, v13
	v_or_b32_e32 v2, 0x53, v9
	v_cmp_gt_i32_e64 s[78:79], v2, v13
	v_or_b32_e32 v2, 0x60, v9
	v_cmp_le_i32_e64 s[82:83], v2, v13
	v_cmp_lt_i32_e64 s[84:85], v2, v13
	v_or_b32_e32 v2, 0x62, v9
	v_cmp_gt_i32_e64 s[86:87], v2, v13
	v_or_b32_e32 v2, 0x63, v9
	v_cmp_gt_i32_e64 s[88:89], v2, v13
	v_or_b32_e32 v2, 0x70, v9
	v_cmp_le_i32_e64 s[92:93], v2, v13
	v_cmp_lt_i32_e64 s[94:95], v2, v13
	v_or_b32_e32 v2, 0x72, v9
	v_writelane_b32 v255, s0, 32
	v_cmp_gt_i32_e64 s[96:97], v2, v13
	v_or_b32_e32 v2, 0x73, v9
	v_writelane_b32 v255, s1, 33
	v_cmp_gt_i32_e64 s[0:1], v2, v13
	v_mul_lo_u32 v2, v10, s8
	v_mad_u32_u24 v2, v113, s2, v2
	s_mov_b32 s2, 0x8800
	v_add3_u32 v130, v2, v160, s2
	v_mul_u32_u24_e32 v2, 0x480, v12
	v_add3_u32 v131, v2, v3, v1
	s_branch .LBB0_503
